# attention unit prologue: tile-0 K/V global loads issued before the unit's first barrier (waits to first consumer)
# baseline (speedup 1.0000x reference)
; #define AT_LOAD(t) do { _Pragma("unroll") for (int i = 0; i < 2; ++i) { const int p = tid + 512 * i; \
;             kr[i] = *(const u32x4*)(kbase + (size_t)((t) * 64 + (p >> 4)) * HP1 + (p & 15) * 8); \
;             vr[i] = *(const u32x4*)(vbase + (size_t)(p >> 3) * R + (t) * 64 + (p & 7) * 8); } } while (0)
; #define AT_STORE(bo) do { _Pragma("unroll") for (int i = 0; i < 2; ++i) { const int p = tid + 512 * i; const int part = p & 15; \
;             *(LAS u32x4*)(lds + (bo) + (part >> 3) * AT_K2 + (p >> 4) * AT_KS + (part & 7) * 16) = kr[i]; \
;             *(LAS u32x4*)(lds + (bo) + AT_V + (p >> 3) * AT_KS + (p & 7) * 16) = vr[i]; } } while (0)
; __device__ __forceinline__ void attn_phase(KA a, lds8* lds, int tid, int lane, int wave) {
;     ...
;         if (it < 1024) { const int rd = it >> 8, b = it & 255; seqb = 0; S = RP; h = 2 * rd + ((b & 7) >> 2); qb = (b >> 3) + 32 * (b & 3); }
;         else { const int u = it - 1024, b = u & 255; seqb = RP + 4096 * (u >> 8); S = 4096; h = b & 7; qb = b >> 3; }
;         const int q0 = seqb + 128 * qb; const int myrow = q0 + 32 * qg + l31;
;         bf16x8 qf[4];
; #pragma unroll
;         for (int ks = 0; ks < 4; ++ks) qf[ks] = *(const bf16x8*)(H + (size_t)myrow * HP1 + 1024 + h * 128 + map * 64 + 16 * ks + 8 * hh);
;         f32x16 O[4], negm = zero16;
; #pragma unroll
;         for (int db = 0; db < 4; ++db) O[db] = zero16;
;         float lsA = 0.f, lsB = 0.f, lsC = 0.f, lsD = 0.f;
;         const int nt = S / 64;
;         u32x4 kr[2], vr[2];
;         const bf16_t* kbase = H + (size_t)seqb * HP1 + 2048 + h * 128; const bf16_t* vbase = VT + (size_t)(h * 128) * R + seqb;
;     ...
;         bf16x8 pf[2][2]; bf16x8 kf[4], vf[8];
;         const unsigned lds0 = (unsigned)(size_t)lds;
;         const unsigned kaddr0 = lds0 + map * AT_K2 + krow_off, vaddr0 = lds0 + AT_V + vrow_off;
;         __syncthreads();
;         AT_LOAD(0); AT_STORE(0);
;         __syncthreads();
.LBB0_1303:
	s_lshl_b32 s8, s15, 7
	s_add_i32 s8, s18, s8
	s_lshl_b32 s52, s14, 7
	v_or_b32_e32 v180, s8, v245
	v_mov_b64_e32 v[0:1], s[16:17]
	s_ashr_i32 s53, s52, 31
	v_mad_u64_u32 v[0:1], s[8:9], v180, s33, v[0:1]
	s_lshl_b64 s[12:13], s[52:53], 1
	s_mul_i32 s61, s18, 0x1800
	s_mul_hi_u32 s37, s18, 0x1800
	s_add_u32 s8, s16, s61
	s_addc_u32 s9, s17, s37
	s_add_u32 s8, s8, s12
	v_lshl_add_u64 v[0:1], v[0:1], 0, s[12:13]
	s_addc_u32 s9, s9, s13
	s_mul_i32 s62, s14, 0xc00000
	v_lshl_add_u64 v[0:1], v[0:1], 0, s[26:27]
	s_mul_hi_i32 s63, s52, 0x18000
	s_add_u32 s14, s10, s62
	v_lshl_add_u64 v[0:1], v[178:179], 1, v[0:1]
	s_addc_u32 s15, s11, s63
	s_lshl_b64 s[54:55], s[18:19], 1
	v_mov_b32_e32 v205, v181
	global_load_dwordx4 v[128:131], v[0:1], off offset:2048
	global_load_dwordx4 v[132:135], v[0:1], off offset:2080
	global_load_dwordx4 v[136:139], v[0:1], off offset:2112
	global_load_dwordx4 v[140:143], v[0:1], off offset:2144
	s_add_u32 s14, s14, s54
	v_lshl_add_u64 v[0:1], s[8:9], 0, v[204:205]
	s_addc_u32 s15, s15, s55
	v_lshl_add_u64 v[0:1], v[0:1], 0, s[28:29]
	v_mov_b32_e32 v207, v181
	v_lshl_add_u64 v[2:3], s[14:15], 0, v[206:207]
	v_lshl_add_u64 v[4:5], v[0:1], 0, v[184:185]
	v_lshl_add_u64 v[0:1], v[0:1], 0, v[188:189]
	v_lshl_add_u64 v[6:7], v[2:3], 0, v[186:187]
	global_load_dwordx4 v[144:147], v[4:5], off
	global_load_dwordx4 v[148:151], v[6:7], off
	v_lshl_add_u64 v[2:3], v[2:3], 0, v[190:191]
	global_load_dwordx4 v[152:155], v[0:1], off
	global_load_dwordx4 v[156:159], v[2:3], off
	s_barrier
	s_add_u32 s8, s12, s61
	s_addc_u32 s9, s13, s37
	s_add_u32 s98, s8, s24
	s_addc_u32 s99, s9, s25
	v_mov_b32_e32 v14, v181
	v_mov_b32_e32 v15, v181
	v_lshl_add_u64 v[212:213], s[8:9], 0, v[196:197]
	v_lshl_add_u64 v[214:215], s[8:9], 0, v[198:199]
	s_add_u32 s8, s54, s62
	v_mov_b32_e32 v208, v181
	v_mov_b32_e32 v209, v181
	v_mov_b32_e32 v0, v181
	v_mov_b32_e32 v1, v181
	v_mov_b32_e32 v2, v181
	v_mov_b32_e32 v3, v181
	v_mov_b32_e32 v4, v181
	v_mov_b32_e32 v5, v181
	v_mov_b32_e32 v6, v181
	v_mov_b32_e32 v7, v181
	v_mov_b32_e32 v8, v181
	v_mov_b32_e32 v9, v181
	v_mov_b32_e32 v10, v181
	v_mov_b32_e32 v11, v181
	v_mov_b32_e32 v12, v181
	v_mov_b32_e32 v13, v181
	v_mov_b64_e32 v[30:31], v[14:15]
	v_mov_b64_e32 v[46:47], v[14:15]
	v_mov_b64_e32 v[62:63], v[14:15]
	v_mov_b64_e32 v[78:79], v[14:15]
	s_addc_u32 s9, s55, s63
	s_add_u32 s100, s8, s24
	s_addc_u32 s101, s9, s25
	v_add_u32_e32 v96, v237, v238
	s_mov_b32 s14, 0x12000
	s_mov_b32 s15, 0
	s_mov_b32 s18, 0
	v_mov_b64_e32 v[28:29], v[12:13]
	v_mov_b64_e32 v[26:27], v[10:11]
	v_mov_b64_e32 v[24:25], v[8:9]
	v_mov_b64_e32 v[22:23], v[6:7]
	v_mov_b64_e32 v[20:21], v[4:5]
	v_mov_b64_e32 v[18:19], v[2:3]
	v_mov_b64_e32 v[16:17], v[0:1]
	v_mov_b64_e32 v[44:45], v[12:13]
	v_mov_b64_e32 v[42:43], v[10:11]
	v_mov_b64_e32 v[40:41], v[8:9]
	v_mov_b64_e32 v[38:39], v[6:7]
	v_mov_b64_e32 v[36:37], v[4:5]
	v_mov_b64_e32 v[34:35], v[2:3]
	v_mov_b64_e32 v[32:33], v[0:1]
	v_mov_b64_e32 v[60:61], v[12:13]
	v_mov_b64_e32 v[58:59], v[10:11]
	v_mov_b64_e32 v[56:57], v[8:9]
	v_mov_b64_e32 v[54:55], v[6:7]
	v_mov_b64_e32 v[52:53], v[4:5]
	v_mov_b64_e32 v[50:51], v[2:3]
	v_mov_b64_e32 v[48:49], v[0:1]
	v_mov_b64_e32 v[76:77], v[12:13]
	v_mov_b64_e32 v[74:75], v[10:11]
	v_mov_b64_e32 v[72:73], v[8:9]
	v_mov_b64_e32 v[70:71], v[6:7]
	v_mov_b64_e32 v[68:69], v[4:5]
	v_mov_b64_e32 v[66:67], v[2:3]
	v_mov_b64_e32 v[64:65], v[0:1]
	v_lshl_add_u64 v[216:217], s[8:9], 0, v[200:201]
	v_lshl_add_u64 v[218:219], s[8:9], 0, v[202:203]
	v_mov_b64_e32 v[210:211], v[208:209]
	v_add_u32_e32 v97, v236, v239
	v_add_u32_e32 v98, v237, v240
	v_add_u32_e32 v99, v236, v241
	s_waitcnt vmcnt(3)
	ds_write_b128 v96, v[144:147]
	s_waitcnt vmcnt(2)
	ds_write_b128 v97, v[148:151] offset:18432
	s_waitcnt vmcnt(1)
	ds_write_b128 v98, v[152:155]
	s_waitcnt vmcnt(0)
	ds_write_b128 v99, v[156:159] offset:18432
	global_load_dwordx4 v[144:147], v198, s[98:99]
	global_load_dwordx4 v[148:151], v202, s[100:101]
	global_load_dwordx4 v[152:155], v196, s[98:99]
	global_load_dwordx4 v[156:159], v200, s[100:101]
	s_waitcnt lgkmcnt(0)
	s_barrier
